# carry fix-up of both passes with packed fma on adjacent elements
# baseline (speedup 1.0000x reference)
; #define LAS __attribute__((address_space(3)))
; __device__ __forceinline__ unsigned cvt_pk_bf16(float lo, float hi) { unsigned r; asm volatile("v_cvt_pk_bf16_f32 %0, %1, %2" : "=v"(r) : "v"(lo), "v"(hi)); return r; }
; __device__ __forceinline__ float bf_lo(unsigned u) { return __uint_as_float(u << 16); }
; __device__ __forceinline__ float bf_hi(unsigned u) { return __uint_as_float(u & 0xffff0000u); }
; __device__ __forceinline__ bf16_t f2bf(float f) { return (bf16_t)(cvt_pk_bf16(f, 0.f) & 0xffffu); }
; #define LDS_BARRIER() do { asm volatile("s_waitcnt lgkmcnt(0)" ::: "memory"); __builtin_amdgcn_s_barrier(); asm volatile("" ::: "memory"); } while (0)
; template <int dir>
; __device__ __forceinline__ void lru_pass(LAS unsigned char* lds, const Params& P, int b, int h, int q, bool dry) {
;     ...
;             LDS_BARRIER();
;             float cin = carry, cend = carry;
; #pragma unroll
;             for (int w = 0; w < 8; ++w) { const float pw = AGG[(w * 2 + 0) * 32 + nl], ew = AGG[(w * 2 + 1) * 32 + nl]; if (w == wid) cin = cend; cend = fmaf(pw, cend, ew); }
;             carry = cend;
;             if (g) cin = fmaf(P0, cin, E0);
;             if (!isctx) {
; #pragma unroll
;                 for (int v = 0; v < 16; ++v) { const float hv = fmaf(zi[v], cin, zr[v]);
;                     const int s = sbase + v; const int tl = dir == 0 ? s : 255 - s;
;                     if (dir == 0) *(LAS unsigned*)(TOUT + tl * IO_WP + nl * 4) = (cvt_pk_bf16(hv, 0.f) & 0xffffu) | (pk[v] << 16);
;                     else *(LAS bf16_t*)(TOUT + tl * IO_NP + nl * 2) = f2bf((bf_lo(pk[v]) + hv) * bf_hi(pk[v])); }
.LBB0_299:
	s_or_b64 exec, exec, s[18:19]
	s_waitcnt lgkmcnt(0)
	s_barrier
	s_setprio 1
	v_add_u32_e32 v34, s99, v140
	ds_read2_b32 v[36:37], v34 offset1:32
	ds_read2_b32 v[38:39], v34 offset0:64 offset1:96
	ds_read2_b32 v[40:41], v34 offset0:128 offset1:160
	ds_read2_b32 v[42:43], v34 offset0:192 offset1:224
	v_add_u32_e32 v32, s100, v140
	ds_read2_b32 v[44:45], v32 offset1:32
	s_waitcnt lgkmcnt(4)
	v_fmac_f32_e32 v37, v36, v165
	ds_read2_b32 v[46:47], v32 offset0:64 offset1:96
	s_waitcnt lgkmcnt(4)
	v_fmac_f32_e32 v39, v38, v37
	ds_read2_b32 v[34:35], v32 offset0:128 offset1:160
	s_waitcnt lgkmcnt(4)
	v_fmac_f32_e32 v41, v40, v39
	ds_read2_b32 v[32:33], v32 offset0:192 offset1:224
	s_waitcnt lgkmcnt(4)
	v_fmac_f32_e32 v43, v42, v41
	s_waitcnt lgkmcnt(3)
	v_fmac_f32_e32 v45, v44, v43
	s_waitcnt lgkmcnt(2)
	v_fmac_f32_e32 v47, v46, v45
	s_cmp_eq_u32 s80, 0
	s_waitcnt lgkmcnt(1)
	v_fmac_f32_e32 v35, v34, v47
	s_cbranch_scc1 .LBB0_301
	v_cndmask_b32_e64 v37, v165, v37, s[14:15]
	v_cndmask_b32_e64 v37, v37, v39, s[12:13]
	v_cndmask_b32_e64 v37, v37, v41, s[10:11]
	v_cndmask_b32_e64 v37, v37, v43, s[8:9]
	v_cndmask_b32_e64 v37, v37, v45, s[4:5]
	v_cndmask_b32_e64 v37, v37, v47, s[16:17]
	v_cndmask_b32_e64 v37, v37, v35, s[0:1]
	v_fmac_f32_e32 v189, v188, v37
	v_cndmask_b32_e32 v34, v189, v37, vcc
	v_fmac_f32_e32 v49, v171, v34
	v_pk_fma_f32 v[172:173], v[50:51], v[34:35], v[172:173] op_sel_hi:[1,0,1]
	v_pk_fma_f32 v[174:175], v[52:53], v[34:35], v[174:175] op_sel_hi:[1,0,1]
	v_pk_fma_f32 v[176:177], v[54:55], v[34:35], v[176:177] op_sel_hi:[1,0,1]
	v_pk_fma_f32 v[178:179], v[56:57], v[34:35], v[178:179] op_sel_hi:[1,0,1]
	v_pk_fma_f32 v[180:181], v[58:59], v[34:35], v[180:181] op_sel_hi:[1,0,1]
	v_pk_fma_f32 v[182:183], v[60:61], v[34:35], v[182:183] op_sel_hi:[1,0,1]
	v_fmac_f32_e32 v184, v62, v34
	v_fmac_f32_e32 v63, v186, v34
	v_fmac_f32_e32 v185, v187, v34
	v_cvt_pk_bf16_f32 v36, v49, v172
	ds_write_b16 v164, v36
	ds_write_b16_d16_hi v164, v36 offset:80
	v_cvt_pk_bf16_f32 v37, v173, v174
	ds_write_b16 v164, v37 offset:160
	ds_write_b16_d16_hi v164, v37 offset:240
	v_cvt_pk_bf16_f32 v38, v175, v176
	ds_write_b16 v164, v38 offset:320
	ds_write_b16_d16_hi v164, v38 offset:400
	v_cvt_pk_bf16_f32 v39, v177, v178
	ds_write_b16 v164, v39 offset:480
	ds_write_b16_d16_hi v164, v39 offset:560
	v_cvt_pk_bf16_f32 v36, v179, v180
	ds_write_b16 v164, v36 offset:640
	ds_write_b16_d16_hi v164, v36 offset:720
	v_cvt_pk_bf16_f32 v37, v181, v182
	ds_write_b16 v164, v37 offset:800
	ds_write_b16_d16_hi v164, v37 offset:880
	v_cvt_pk_bf16_f32 v38, v183, v184
	ds_write_b16 v164, v38 offset:960
	ds_write_b16_d16_hi v164, v38 offset:1040
	v_cvt_pk_bf16_f32 v39, v63, v185
	ds_write_b16 v164, v39 offset:1120
	ds_write_b16_d16_hi v164, v39 offset:1200

; #define LAS __attribute__((address_space(3)))
; __device__ __forceinline__ unsigned cvt_pk_bf16(float lo, float hi) { unsigned r; asm volatile("v_cvt_pk_bf16_f32 %0, %1, %2" : "=v"(r) : "v"(lo), "v"(hi)); return r; }
; __device__ __forceinline__ float bf_lo(unsigned u) { return __uint_as_float(u << 16); }
; __device__ __forceinline__ float bf_hi(unsigned u) { return __uint_as_float(u & 0xffff0000u); }
; __device__ __forceinline__ bf16_t f2bf(float f) { return (bf16_t)(cvt_pk_bf16(f, 0.f) & 0xffffu); }
; #define LDS_BARRIER() do { asm volatile("s_waitcnt lgkmcnt(0)" ::: "memory"); __builtin_amdgcn_s_barrier(); asm volatile("" ::: "memory"); } while (0)
; template <int dir>
; __device__ __forceinline__ void lru_pass(LAS unsigned char* lds, const Params& P, int b, int h, int q, bool dry) {
;     ...
;             LDS_BARRIER();
;             float cin = carry, cend = carry;
; #pragma unroll
;             for (int w = 0; w < 8; ++w) { const float pw = AGG[(w * 2 + 0) * 32 + nl], ew = AGG[(w * 2 + 1) * 32 + nl]; if (w == wid) cin = cend; cend = fmaf(pw, cend, ew); }
;             carry = cend;
;             if (g) cin = fmaf(P0, cin, E0);
;             if (!isctx) {
; #pragma unroll
;                 for (int v = 0; v < 16; ++v) { const float hv = fmaf(zi[v], cin, zr[v]);
;                     const int s = sbase + v; const int tl = dir == 0 ? s : 255 - s;
;                     if (dir == 0) *(LAS unsigned*)(TOUT + tl * IO_WP + nl * 4) = (cvt_pk_bf16(hv, 0.f) & 0xffffu) | (pk[v] << 16);
;                     else *(LAS bf16_t*)(TOUT + tl * IO_NP + nl * 2) = f2bf((bf_lo(pk[v]) + hv) * bf_hi(pk[v])); }
.LBB0_313:
	s_or_b64 exec, exec, s[18:19]
	s_waitcnt lgkmcnt(0)
	s_barrier
	s_setprio 1
	v_add_u32_e32 v34, s99, v161
	ds_read2_b32 v[36:37], v34 offset1:32
	ds_read2_b32 v[38:39], v34 offset0:64 offset1:96
	ds_read2_b32 v[40:41], v34 offset0:128 offset1:160
	ds_read2_b32 v[42:43], v34 offset0:192 offset1:224
	v_add_u32_e32 v32, s100, v161
	s_waitcnt lgkmcnt(3)
	v_fmac_f32_e32 v37, v36, v222
	s_waitcnt lgkmcnt(2)
	v_fmac_f32_e32 v39, v38, v37
	s_waitcnt lgkmcnt(1)
	v_fmac_f32_e32 v41, v40, v39
	ds_read2_b32 v[44:45], v32 offset1:32
	ds_read2_b32 v[46:47], v32 offset0:64 offset1:96
	ds_read2_b32 v[34:35], v32 offset0:128 offset1:160
	ds_read2_b32 v[32:33], v32 offset0:192 offset1:224
	s_waitcnt lgkmcnt(4)
	v_fmac_f32_e32 v43, v42, v41
	s_waitcnt lgkmcnt(3)
	v_fmac_f32_e32 v45, v44, v43
	s_waitcnt lgkmcnt(2)
	v_fmac_f32_e32 v47, v46, v45
	s_cmp_eq_u32 s44, 0
	s_waitcnt lgkmcnt(1)
	v_fmac_f32_e32 v35, v34, v47
	s_cbranch_scc1 .LBB0_315
	v_cndmask_b32_e64 v37, v222, v37, s[14:15]
	v_cndmask_b32_e64 v37, v37, v39, s[12:13]
	v_cndmask_b32_e64 v37, v37, v41, s[10:11]
	v_cndmask_b32_e64 v37, v37, v43, s[8:9]
	v_cndmask_b32_e64 v37, v37, v45, s[4:5]
	v_cndmask_b32_e64 v37, v37, v47, s[16:17]
	v_cndmask_b32_e64 v37, v37, v35, s[0:1]
	v_fmac_f32_e32 v245, v244, v37
	v_cndmask_b32_e32 v34, v245, v37, vcc
	v_fmac_f32_e32 v49, v227, v34
	v_pk_fma_f32 v[228:229], v[50:51], v[34:35], v[228:229] op_sel_hi:[1,0,1]
	v_pk_fma_f32 v[230:231], v[52:53], v[34:35], v[230:231] op_sel_hi:[1,0,1]
	v_pk_fma_f32 v[232:233], v[54:55], v[34:35], v[232:233] op_sel_hi:[1,0,1]
	v_pk_fma_f32 v[234:235], v[56:57], v[34:35], v[234:235] op_sel_hi:[1,0,1]
	v_pk_fma_f32 v[236:237], v[58:59], v[34:35], v[236:237] op_sel_hi:[1,0,1]
	v_pk_fma_f32 v[238:239], v[60:61], v[34:35], v[238:239] op_sel_hi:[1,0,1]
	v_fmac_f32_e32 v240, v62, v34
	v_fmac_f32_e32 v63, v243, v34
	v_fmac_f32_e32 v241, v242, v34
	v_lshlrev_b32_e32 v36, 16, v226
	v_lshlrev_b32_e32 v38, 16, v225
	v_add_f32_e32 v36, v49, v36
	v_add_f32_e32 v38, v228, v38
	v_and_b32_e32 v37, 0xffff0000, v226
	v_and_b32_e32 v39, 0xffff0000, v225
	v_mul_f32_e32 v36, v36, v37
	v_mul_f32_e32 v38, v38, v39
	v_cvt_pk_bf16_f32 v36, v36, v38
	ds_write_b16 v206, v36
	ds_write_b16_d16_hi v207, v36
	v_lshlrev_b32_e32 v40, 16, v224
	v_lshlrev_b32_e32 v42, 16, v223
	v_add_f32_e32 v40, v229, v40
	v_add_f32_e32 v42, v230, v42
	v_and_b32_e32 v41, 0xffff0000, v224
	v_and_b32_e32 v43, 0xffff0000, v223
	v_mul_f32_e32 v40, v40, v41
	v_mul_f32_e32 v42, v42, v43
	v_cvt_pk_bf16_f32 v40, v40, v42
	ds_write_b16 v208, v40
	ds_write_b16_d16_hi v209, v40
	v_lshlrev_b32_e32 v36, 16, v135
	v_lshlrev_b32_e32 v38, 16, v134
	v_add_f32_e32 v36, v231, v36
	v_add_f32_e32 v38, v232, v38
	v_and_b32_e32 v37, 0xffff0000, v135
	v_and_b32_e32 v39, 0xffff0000, v134
	v_mul_f32_e32 v36, v36, v37
	v_mul_f32_e32 v38, v38, v39
	v_cvt_pk_bf16_f32 v36, v36, v38
	ds_write_b16 v210, v36
	ds_write_b16_d16_hi v211, v36
	v_lshlrev_b32_e32 v40, 16, v133
	v_lshlrev_b32_e32 v42, 16, v131
	v_add_f32_e32 v40, v233, v40
	v_add_f32_e32 v42, v234, v42
	v_and_b32_e32 v41, 0xffff0000, v133
	v_and_b32_e32 v43, 0xffff0000, v131
	v_mul_f32_e32 v40, v40, v41
	v_mul_f32_e32 v42, v42, v43
	v_cvt_pk_bf16_f32 v40, v40, v42
	ds_write_b16 v212, v40
	ds_write_b16_d16_hi v213, v40
	v_lshlrev_b32_e32 v36, 16, v132
	v_lshlrev_b32_e32 v38, 16, v130
	v_add_f32_e32 v36, v235, v36
	v_add_f32_e32 v38, v236, v38
	v_and_b32_e32 v37, 0xffff0000, v132
	v_and_b32_e32 v39, 0xffff0000, v130
	v_mul_f32_e32 v36, v36, v37
	v_mul_f32_e32 v38, v38, v39
	v_cvt_pk_bf16_f32 v36, v36, v38
	ds_write_b16 v214, v36
	ds_write_b16_d16_hi v215, v36
	v_lshlrev_b32_e32 v40, 16, v129
	v_lshlrev_b32_e32 v42, 16, v128
	v_add_f32_e32 v40, v237, v40
	v_add_f32_e32 v42, v238, v42
	v_and_b32_e32 v41, 0xffff0000, v129
	v_and_b32_e32 v43, 0xffff0000, v128
	v_mul_f32_e32 v40, v40, v41
	v_mul_f32_e32 v42, v42, v43
	v_cvt_pk_bf16_f32 v40, v40, v42
	ds_write_b16 v216, v40
	ds_write_b16_d16_hi v217, v40
	v_lshlrev_b32_e32 v36, 16, v67
	v_lshlrev_b32_e32 v38, 16, v66
	v_add_f32_e32 v36, v239, v36
	v_add_f32_e32 v38, v240, v38
	v_and_b32_e32 v37, 0xffff0000, v67
	v_and_b32_e32 v39, 0xffff0000, v66
	v_mul_f32_e32 v36, v36, v37
	v_mul_f32_e32 v38, v38, v39
	v_cvt_pk_bf16_f32 v36, v36, v38
	ds_write_b16 v218, v36
	ds_write_b16_d16_hi v219, v36
	v_lshlrev_b32_e32 v40, 16, v64
	v_lshlrev_b32_e32 v42, 16, v251
	v_add_f32_e32 v40, v63, v40
	v_add_f32_e32 v42, v241, v42
	v_and_b32_e32 v41, 0xffff0000, v64
	v_and_b32_e32 v43, 0xffff0000, v251
	v_mul_f32_e32 v40, v40, v41
	v_mul_f32_e32 v42, v42, v43
	v_cvt_pk_bf16_f32 v40, v40, v42
	ds_write_b16 v220, v40
	ds_write_b16_d16_hi v221, v40
